# v48 + the same depth-4 max3 tree for the row-max in the two context-attention softmax loops (bit-identical)
# baseline (speedup 1.0000x reference)
.LBB0_663:
	s_add_i32 s4, s14, 0
	v_add3_u32 v2, s4, v145, v144
	ds_read_b128 v[68:71], v2 offset:32768
	ds_read_b128 v[72:75], v2 offset:40960
	v_add3_u32 v2, s4, v146, v144
	ds_read_b128 v[160:163], v2 offset:32768
	ds_read_b128 v[164:167], v2 offset:40960
	v_add3_u32 v2, s4, v147, v144
	s_waitcnt lgkmcnt(0)
	v_mfma_f32_32x32x16_bf16 v[84:99], v[68:71], v[100:103], 0
	s_add_i32 s5, s7, 0
	s_add_i32 s5, s5, 0x10000
	v_mfma_f32_32x32x16_bf16 v[68:83], v[72:75], v[100:103], 0
	v_mfma_f32_32x32x16_bf16 v[84:99], v[160:163], v[104:107], v[84:99]
	v_mfma_f32_32x32x16_bf16 v[68:83], v[164:167], v[104:107], v[68:83]
	ds_read_b128 v[160:163], v2 offset:32768
	ds_read_b128 v[164:167], v2 offset:40960
	v_add3_u32 v2, s4, v151, v144
	s_waitcnt lgkmcnt(0)
	v_mfma_f32_32x32x16_bf16 v[84:99], v[160:163], v[108:111], v[84:99]
	v_mfma_f32_32x32x16_bf16 v[68:83], v[164:167], v[108:111], v[68:83]
	ds_read_b128 v[160:163], v2 offset:32768
	ds_read_b128 v[164:167], v2 offset:40960
	v_add3_u32 v2, s4, v152, v144
	s_waitcnt lgkmcnt(0)
	v_mfma_f32_32x32x16_bf16 v[84:99], v[160:163], v[112:115], v[84:99]
	v_mfma_f32_32x32x16_bf16 v[68:83], v[164:167], v[112:115], v[68:83]
	ds_read_b128 v[160:163], v2 offset:32768
	ds_read_b128 v[164:167], v2 offset:40960
	v_add3_u32 v2, s4, v153, v144
	s_waitcnt lgkmcnt(0)
	v_mfma_f32_32x32x16_bf16 v[84:99], v[160:163], v[116:119], v[84:99]
	v_mfma_f32_32x32x16_bf16 v[68:83], v[164:167], v[116:119], v[68:83]
	ds_read_b128 v[160:163], v2 offset:32768
	ds_read_b128 v[164:167], v2 offset:40960
	v_add3_u32 v2, s4, v154, v144
	s_waitcnt lgkmcnt(0)
	v_mfma_f32_32x32x16_bf16 v[84:99], v[160:163], v[120:123], v[84:99]
	v_mfma_f32_32x32x16_bf16 v[68:83], v[164:167], v[120:123], v[68:83]
	ds_read_b128 v[160:163], v2 offset:32768
	ds_read_b128 v[164:167], v2 offset:40960
	v_add3_u32 v2, s4, v155, v144
	s_mov_b32 s4, 0x42ddb3d8
	s_waitcnt lgkmcnt(0)
	v_mfma_f32_32x32x16_bf16 v[84:99], v[160:163], v[124:127], v[84:99]
	v_mfma_f32_32x32x16_bf16 v[68:83], v[164:167], v[124:127], v[68:83]
	ds_read_b128 v[160:163], v2 offset:32768
	ds_read_b128 v[164:167], v2 offset:40960
	v_add3_u32 v2, s5, v145, v156
	s_waitcnt lgkmcnt(0)
	v_mfma_f32_32x32x16_bf16 v[84:99], v[160:163], v[128:131], v[84:99]
	v_mfma_f32_32x32x16_bf16 v[68:83], v[164:167], v[128:131], v[68:83]
	ds_read_b128 v[160:163], v2
	ds_read_b128 v[164:167], v2 offset:4096
	ds_read_b128 v[168:171], v176
	v_add3_u32 v2, s5, v146, v156
	s_waitcnt lgkmcnt(0)
	v_mfma_f32_32x32x16_bf16 v[84:99], v[160:163], v[168:171], v[84:99]
	v_mfma_f32_32x32x16_bf16 v[68:83], v[164:167], v[168:171], v[68:83]
	ds_read_b128 v[160:163], v2
	ds_read_b128 v[164:167], v2 offset:4096
	ds_read_b128 v[168:171], v176 offset:1024
	v_add3_u32 v2, s5, v147, v156
	s_waitcnt lgkmcnt(0)
	v_mfma_f32_32x32x16_bf16 v[84:99], v[160:163], v[168:171], v[84:99]
	v_mfma_f32_32x32x16_bf16 v[68:83], v[164:167], v[168:171], v[68:83]
	ds_read_b128 v[160:163], v2
	ds_read_b128 v[164:167], v2 offset:4096
	ds_read_b128 v[168:171], v176 offset:2048
	v_add3_u32 v2, s5, v151, v156
	s_waitcnt lgkmcnt(0)
	v_mfma_f32_32x32x16_bf16 v[84:99], v[160:163], v[168:171], v[84:99]
	v_mfma_f32_32x32x16_bf16 v[68:83], v[164:167], v[168:171], v[68:83]
	ds_read_b128 v[160:163], v2
	ds_read_b128 v[164:167], v2 offset:4096
	ds_read_b128 v[168:171], v176 offset:3072
	s_waitcnt lgkmcnt(0)
	v_mfma_f32_32x32x16_bf16 v[84:99], v[160:163], v[168:171], v[84:99]
	v_mfma_f32_32x32x16_bf16 v[68:83], v[164:167], v[168:171], v[68:83]
	s_nop 10
	v_max_f32_e32 v2, v85, v85
	v_max_f32_e32 v160, v84, v84
	v_max3_f32 v226, v2, v160, v86
	v_max3_f32 v227, v87, v88, v89
	v_max3_f32 v228, v90, v91, v92
	v_max3_f32 v229, v93, v94, v95
	v_max3_f32 v230, v96, v97, v98
	v_max3_f32 v226, v226, v227, v228
	v_max3_f32 v229, v229, v230, v99
	s_nop 0
	v_max3_f32 v227, v68, v69, v70
	v_max3_f32 v228, v71, v72, v73
	v_max3_f32 v230, v74, v75, v76
	v_max3_f32 v231, v77, v78, v79
	v_max3_f32 v232, v80, v81, v82
	v_max3_f32 v227, v227, v228, v230
	v_max3_f32 v231, v231, v232, v83
	v_max3_f32 v226, v226, v229, v227
	v_max_f32_e32 v2, v226, v231
	v_mov_b32_e32 v160, v2
	s_nop 1
	v_permlane32_swap_b32_e32 v2, v160
	v_max_f32_e32 v160, v160, v160
	v_max_f32_e32 v2, v2, v2
	v_max_f32_e32 v2, v2, v160
	v_sub_f32_e32 v160, v2, v158
	v_cmp_ge_f32_e32 vcc, s4, v160
	v_max_f32_e32 v160, v158, v158
	v_max_f32_e32 v160, v160, v2
	v_sub_f32_e32 v2, v158, v160
	v_mul_f32_e32 v2, 0x3dd53b94, v2
	v_exp_f32_e32 v2, v2
	s_cmp_eq_u64 vcc, exec
	s_cselect_b64 s[4:5], -1, 0
	v_cndmask_b32_e64 v2, v2, 1.0, s[4:5]
	v_cmp_gt_f32_e32 vcc, 1.0, v2
	s_cbranch_vccz .LBB0_667
	s_and_saveexec_b64 s[6:7], s[0:1]
	ds_write_b32 v150, v2 offset:128
	s_or_b64 exec, exec, s[6:7]
	s_waitcnt lgkmcnt(0)
	ds_read_b128 v[162:165], v142 offset:224
	ds_read_b128 v[166:169], v142 offset:192
	ds_read_b128 v[170:173], v142 offset:160
	ds_read_b128 v[178:181], v142 offset:128
	s_waitcnt lgkmcnt(0)
	v_pk_mul_f32 v[66:67], v[66:67], v[164:165]
	v_pk_mul_f32 v[62:63], v[62:63], v[168:169]
	v_pk_mul_f32 v[58:59], v[58:59], v[172:173]
	v_pk_mul_f32 v[54:55], v[54:55], v[180:181]
	v_pk_mul_f32 v[64:65], v[64:65], v[162:163]
	v_pk_mul_f32 v[60:61], v[60:61], v[166:167]
	v_pk_mul_f32 v[56:57], v[56:57], v[170:171]
	v_pk_mul_f32 v[52:53], v[52:53], v[178:179]
	v_pk_mul_f32 v[50:51], v[50:51], v[164:165]
	v_pk_mul_f32 v[46:47], v[46:47], v[168:169]
	v_pk_mul_f32 v[42:43], v[42:43], v[172:173]
	v_pk_mul_f32 v[38:39], v[38:39], v[180:181]
	v_pk_mul_f32 v[48:49], v[48:49], v[162:163]
	v_pk_mul_f32 v[44:45], v[44:45], v[166:167]
	v_pk_mul_f32 v[40:41], v[40:41], v[170:171]
	v_pk_mul_f32 v[36:37], v[36:37], v[178:179]
	v_pk_mul_f32 v[34:35], v[34:35], v[164:165]
	v_pk_mul_f32 v[30:31], v[30:31], v[168:169]
	v_pk_mul_f32 v[26:27], v[26:27], v[172:173]
	v_pk_mul_f32 v[22:23], v[22:23], v[180:181]
	v_pk_mul_f32 v[32:33], v[32:33], v[162:163]
	v_pk_mul_f32 v[28:29], v[28:29], v[166:167]
	v_pk_mul_f32 v[24:25], v[24:25], v[170:171]
	v_pk_mul_f32 v[20:21], v[20:21], v[178:179]
	v_pk_mul_f32 v[18:19], v[18:19], v[164:165]
	v_pk_mul_f32 v[14:15], v[14:15], v[168:169]
	v_pk_mul_f32 v[10:11], v[10:11], v[172:173]
	v_pk_mul_f32 v[6:7], v[6:7], v[180:181]
	v_pk_mul_f32 v[16:17], v[16:17], v[162:163]
	v_pk_mul_f32 v[12:13], v[12:13], v[166:167]
	v_pk_mul_f32 v[8:9], v[8:9], v[170:171]
	v_pk_mul_f32 v[4:5], v[4:5], v[178:179]

.LBB0_681:
	s_add_i32 s4, s19, 0
	v_add3_u32 v2, s4, v144, v143
	ds_read_b128 v[68:71], v2 offset:32768
	ds_read_b128 v[72:75], v2 offset:40960
	v_add3_u32 v2, s4, v145, v143
	ds_read_b128 v[158:161], v2 offset:32768
	ds_read_b128 v[162:165], v2 offset:40960
	v_add3_u32 v2, s4, v147, v143
	s_waitcnt lgkmcnt(0)
	v_mfma_f32_32x32x16_bf16 v[84:99], v[68:71], v[100:103], 0
	v_mfma_f32_32x32x16_bf16 v[68:83], v[72:75], v[100:103], 0
	v_mfma_f32_32x32x16_bf16 v[84:99], v[158:161], v[104:107], v[84:99]
	v_mfma_f32_32x32x16_bf16 v[68:83], v[162:165], v[104:107], v[68:83]
	ds_read_b128 v[158:161], v2 offset:32768
	ds_read_b128 v[162:165], v2 offset:40960
	v_add3_u32 v2, s4, v149, v143
	s_waitcnt lgkmcnt(0)
	v_mfma_f32_32x32x16_bf16 v[84:99], v[158:161], v[108:111], v[84:99]
	v_mfma_f32_32x32x16_bf16 v[68:83], v[162:165], v[108:111], v[68:83]
	ds_read_b128 v[158:161], v2 offset:32768
	ds_read_b128 v[162:165], v2 offset:40960
	v_add3_u32 v2, s4, v150, v143
	s_waitcnt lgkmcnt(0)
	v_mfma_f32_32x32x16_bf16 v[84:99], v[158:161], v[112:115], v[84:99]
	v_mfma_f32_32x32x16_bf16 v[68:83], v[162:165], v[112:115], v[68:83]
	ds_read_b128 v[158:161], v2 offset:32768
	ds_read_b128 v[162:165], v2 offset:40960
	v_add3_u32 v2, s4, v151, v143
	s_waitcnt lgkmcnt(0)
	v_mfma_f32_32x32x16_bf16 v[84:99], v[158:161], v[116:119], v[84:99]
	v_mfma_f32_32x32x16_bf16 v[68:83], v[162:165], v[116:119], v[68:83]
	ds_read_b128 v[158:161], v2 offset:32768
	ds_read_b128 v[162:165], v2 offset:40960
	v_add3_u32 v2, s4, v152, v143
	s_waitcnt lgkmcnt(0)
	v_mfma_f32_32x32x16_bf16 v[84:99], v[158:161], v[120:123], v[84:99]
	v_mfma_f32_32x32x16_bf16 v[68:83], v[162:165], v[120:123], v[68:83]
	ds_read_b128 v[158:161], v2 offset:32768
	ds_read_b128 v[162:165], v2 offset:40960
	v_add3_u32 v2, s4, v153, v143
	s_mov_b32 s4, 0x42b504f3
	s_waitcnt lgkmcnt(0)
	v_mfma_f32_32x32x16_bf16 v[84:99], v[158:161], v[124:127], v[84:99]
	v_mfma_f32_32x32x16_bf16 v[68:83], v[162:165], v[124:127], v[68:83]
	ds_read_b128 v[158:161], v2 offset:32768
	ds_read_b128 v[162:165], v2 offset:40960
	s_waitcnt lgkmcnt(0)
	v_mfma_f32_32x32x16_bf16 v[84:99], v[158:161], v[128:131], v[84:99]
	v_mfma_f32_32x32x16_bf16 v[68:83], v[162:165], v[128:131], v[68:83]
	s_nop 10
	v_max_f32_e32 v2, v85, v85
	v_max_f32_e32 v157, v84, v84
	v_max3_f32 v226, v2, v157, v86
	v_max3_f32 v227, v87, v88, v89
	v_max3_f32 v228, v90, v91, v92
	v_max3_f32 v229, v93, v94, v95
	v_max3_f32 v230, v96, v97, v98
	v_max3_f32 v226, v226, v227, v228
	v_max3_f32 v229, v229, v230, v99
	s_nop 0
	v_max3_f32 v227, v68, v69, v70
	v_max3_f32 v228, v71, v72, v73
	v_max3_f32 v230, v74, v75, v76
	v_max3_f32 v231, v77, v78, v79
	v_max3_f32 v232, v80, v81, v82
	v_max3_f32 v227, v227, v228, v230
	v_max3_f32 v231, v231, v232, v83
	v_max3_f32 v226, v226, v229, v227
	v_max_f32_e32 v2, v226, v231
	v_mov_b32_e32 v157, v2
	s_nop 1
	v_permlane32_swap_b32_e32 v2, v157
	v_max_f32_e32 v157, v157, v157
	v_max_f32_e32 v2, v2, v2
	v_max_f32_e32 v2, v2, v157
	v_sub_f32_e32 v157, v2, v155
	v_cmp_ge_f32_e32 vcc, s4, v157
	v_max_f32_e32 v157, v155, v155
	v_max_f32_e32 v157, v157, v2
	v_sub_f32_e32 v2, v155, v157
	v_mul_f32_e32 v2, 0x3e0293ee, v2
	v_exp_f32_e32 v2, v2
	s_cmp_eq_u64 vcc, exec
	s_cselect_b64 s[4:5], -1, 0
	v_cndmask_b32_e64 v2, v2, 1.0, s[4:5]
	v_cmp_gt_f32_e32 vcc, 1.0, v2
	s_cbranch_vccz .LBB0_685
	s_and_saveexec_b64 s[12:13], s[0:1]
	ds_write_b32 v146, v2 offset:128
	s_or_b64 exec, exec, s[12:13]
	s_waitcnt lgkmcnt(0)
	ds_read_b128 v[158:161], v141 offset:224
	ds_read_b128 v[162:165], v141 offset:192
	ds_read_b128 v[166:169], v141 offset:160
	ds_read_b128 v[170:173], v141 offset:128
	s_waitcnt lgkmcnt(0)
	v_pk_mul_f32 v[66:67], v[66:67], v[160:161]
	v_pk_mul_f32 v[62:63], v[62:63], v[164:165]
	v_pk_mul_f32 v[58:59], v[58:59], v[168:169]
	v_pk_mul_f32 v[54:55], v[54:55], v[172:173]
	v_pk_mul_f32 v[64:65], v[64:65], v[158:159]
	v_pk_mul_f32 v[60:61], v[60:61], v[162:163]
	v_pk_mul_f32 v[56:57], v[56:57], v[166:167]
	v_pk_mul_f32 v[52:53], v[52:53], v[170:171]
	v_pk_mul_f32 v[50:51], v[50:51], v[160:161]
	v_pk_mul_f32 v[46:47], v[46:47], v[164:165]
	v_pk_mul_f32 v[42:43], v[42:43], v[168:169]
	v_pk_mul_f32 v[38:39], v[38:39], v[172:173]
	v_pk_mul_f32 v[48:49], v[48:49], v[158:159]
	v_pk_mul_f32 v[44:45], v[44:45], v[162:163]
	v_pk_mul_f32 v[40:41], v[40:41], v[166:167]
	v_pk_mul_f32 v[36:37], v[36:37], v[170:171]
	v_pk_mul_f32 v[34:35], v[34:35], v[160:161]
	v_pk_mul_f32 v[30:31], v[30:31], v[164:165]
	v_pk_mul_f32 v[26:27], v[26:27], v[168:169]
	v_pk_mul_f32 v[22:23], v[22:23], v[172:173]
	v_pk_mul_f32 v[32:33], v[32:33], v[158:159]
	v_pk_mul_f32 v[28:29], v[28:29], v[162:163]
	v_pk_mul_f32 v[24:25], v[24:25], v[166:167]
	v_pk_mul_f32 v[20:21], v[20:21], v[170:171]
	v_pk_mul_f32 v[18:19], v[18:19], v[160:161]
	v_pk_mul_f32 v[14:15], v[14:15], v[164:165]
	v_pk_mul_f32 v[10:11], v[10:11], v[168:169]
	v_pk_mul_f32 v[6:7], v[6:7], v[172:173]
	v_pk_mul_f32 v[16:17], v[16:17], v[158:159]
	v_pk_mul_f32 v[12:13], v[12:13], v[162:163]
	v_pk_mul_f32 v[8:9], v[8:9], v[166:167]
	v_pk_mul_f32 v[4:5], v[4:5], v[170:171]
